# deferred transposes: ten start slots (b>>3)%10 instead of eight
# baseline (speedup 1.0000x reference)
.LBB0_289:
	s_sub_u32 s0, s94, s86
	s_bfe_u32 s1, s86, 0x50003
	s_mul_i32 s2, s1, 0xcd
	s_lshr_b32 s2, s2, 11
	s_mul_i32 s2, s2, 10
	s_sub_u32 s1, s1, s2
	s_mul_i32 s1, s1, s84
	s_cmp_lg_u32 s0, s1
	s_cbranch_scc1 .Ldt0_skip
	s_mov_b32 s52, s86
	s_cmpk_lg_u32 s84, 0x100
	s_cbranch_scc1 .Ldt0_nrot
	s_xor_b32 s52, s52, 0x80
.Ldt0_nrot:
	s_addk_i32 s52, 0xa08
	s_movk_i32 s9, 0x1c10
	s_cmp_ge_u32 s52, s9
	s_cbranch_scc1 .Ldt0_skip
	s_waitcnt lgkmcnt(0)
	s_barrier
	v_readlane_b32 s54, v254, 54
	v_readlane_b32 s55, v254, 55
	v_readlane_b32 s56, v253, 2
	v_readlane_b32 s57, v253, 3
	v_readlane_b32 s58, v253, 8
	v_readlane_b32 s59, v253, 9
	v_readlane_b32 s60, v253, 10
	v_readlane_b32 s61, v253, 11
	v_readlane_b32 s62, v254, 12
	v_readlane_b32 s63, v254, 13
	v_and_b32_e32 v106, 7, v180
	v_lshrrev_b32_e32 v93, 3, v180
	s_add_u32 s54, s54, 0xa080000
	s_addc_u32 s55, s55, 0
	s_add_u32 s58, s58, 0x5000000
	s_addc_u32 s59, s59, 0
	s_add_u32 s60, s60, 0x40000
	s_addc_u32 s61, s61, 0
	v_lshlrev_b32_e32 v94, 4, v106
	v_bfe_u32 v107, v180, 3, 1
	v_lshlrev_b32_e32 v108, 2, v106
	v_lshl_add_u32 v108, v107, 1, v108
	v_mul_u32_u24_e32 v84, 0x410, v108
	v_lshrrev_b32_e32 v109, 3, v93
	v_xor_b32_e32 v109, v109, v106
	v_lshlrev_b32_e32 v109, 3, v109
	v_and_b32_e32 v110, 6, v93
	v_or_b32_e32 v109, v109, v110
	v_lshl_add_u32 v84, v109, 1, v84
	v_cmp_ne_u32_e64 s[74:75], 0, v107
	v_mov_b32_e32 v104, 0x1000504
	v_mov_b32_e32 v105, 0x3020706
	v_mov_b32_e32 v111, 0x5040100
	v_mov_b32_e32 v112, 0x7060302
	v_cndmask_b32_e64 v104, v104, v111, s[74:75]
	v_cndmask_b32_e64 v105, v105, v112, s[74:75]
	v_lshrrev_b32_e32 v106, 6, v180
	v_and_b32_e32 v107, 63, v180
	v_lshrrev_b32_e32 v108, 2, v106
	v_add_u32_e32 v109, 0, v108
	v_xor_b32_e32 v109, v109, v107
	v_lshlrev_b32_e32 v109, 4, v109
	v_add_u32_e32 v110, 0, v106
	v_mul_u32_u24_e32 v110, 0x410, v110
	v_add_u32_e32 v85, v109, v110
	v_add_u32_e32 v109, 2, v108
	v_xor_b32_e32 v109, v109, v107
	v_lshlrev_b32_e32 v109, 4, v109
	v_add_u32_e32 v110, 8, v106
	v_mul_u32_u24_e32 v110, 0x410, v110
	v_add_u32_e32 v86, v109, v110
	v_add_u32_e32 v109, 4, v108
	v_xor_b32_e32 v109, v109, v107
	v_lshlrev_b32_e32 v109, 4, v109
	v_add_u32_e32 v110, 16, v106
	v_mul_u32_u24_e32 v110, 0x410, v110
	v_add_u32_e32 v87, v109, v110
	v_add_u32_e32 v109, 6, v108
	v_xor_b32_e32 v109, v109, v107
	v_lshlrev_b32_e32 v109, 4, v109
	v_add_u32_e32 v110, 24, v106
	v_mul_u32_u24_e32 v110, 0x410, v110
	v_add_u32_e32 v88, v109, v110
	v_lshlrev_b32_e32 v109, 13, v106
	v_lshl_add_u32 v89, v107, 4, v109
	v_add_u32_e32 v90, 0x10000, v89
	v_add_u32_e32 v91, 0x20000, v89
	v_add_u32_e32 v92, 0x30000, v89
	s_mov_b32 s53, 0
	s_mov_b32 s73, 0
	s_cmpk_ge_u32 s52, 0x1410
	s_cbranch_scc1 .Ldt0_out0
	s_sub_i32 s0, s52, 0xa08
	s_mul_i32 s1, s0, 0xcc3
	s_lshr_b32 s1, s1, 20
	s_mul_i32 s2, s1, 0x141
	s_sub_u32 s2, s0, s2
	s_lshl_b32 s3, s2, 7
	s_mul_i32 s4, s1, 0x1410000
	s_add_u32 s3, s3, s4
	s_add_u32 s64, s54, s3
	s_addc_u32 s65, s55, 0
	s_mov_b32 s7, 0xa080
	s_lshl_b32 s4, s1, 10
	s_cmpk_lt_u32 s2, 0x80
	s_cbranch_scc1 .Ldt0_wlo0
	s_cmpk_eq_u32 s2, 0x80
	s_cbranch_scc1 .Ldt0_wlr0
	s_add_i32 s2, s2, -1

.Ldt0_ud0:
	v_mul_u32_u24_e32 v96, s7, v93
	s_lshl_b32 s6, s7, 6
	v_add_u32_e32 v96, v96, v94
	v_add_u32_e32 v97, s6, v96
	v_add_u32_e32 v98, s6, v97
	v_add_u32_e32 v99, s6, v98
	v_add_u32_e32 v100, s6, v99
	v_add_u32_e32 v101, s6, v100
	v_add_u32_e32 v102, s6, v101
	v_add_u32_e32 v103, s6, v102
	global_load_dwordx4 v[4:7], v96, s[64:65] nt
	global_load_dwordx4 v[8:11], v97, s[64:65] nt
	global_load_dwordx4 v[12:15], v98, s[64:65] nt
	global_load_dwordx4 v[16:19], v99, s[64:65] nt
	global_load_dwordx4 v[20:23], v100, s[64:65] nt
	global_load_dwordx4 v[24:27], v101, s[64:65] nt
	global_load_dwordx4 v[28:31], v102, s[64:65] nt
	global_load_dwordx4 v[32:35], v103, s[64:65] nt
	s_mov_b32 s72, 1
	s_add_u32 s52, s52, s84
	s_cmp_ge_u32 s52, s9
	s_cbranch_scc1 .Ldt0_procA
	s_cmpk_ge_u32 s52, 0x1410
	s_cbranch_scc1 .Ldt0_out1
	s_sub_i32 s0, s52, 0xa08
	s_mul_i32 s1, s0, 0xcc3
	s_lshr_b32 s1, s1, 20
	s_mul_i32 s2, s1, 0x141
	s_sub_u32 s2, s0, s2
	s_lshl_b32 s3, s2, 7
	s_mul_i32 s4, s1, 0x1410000
	s_add_u32 s3, s3, s4
	s_add_u32 s68, s54, s3
	s_addc_u32 s69, s55, 0
	s_mov_b32 s7, 0xa080
	s_lshl_b32 s4, s1, 10
	s_cmpk_lt_u32 s2, 0x80
	s_cbranch_scc1 .Ldt0_wlo1
	s_cmpk_eq_u32 s2, 0x80
	s_cbranch_scc1 .Ldt0_wlr1
	s_add_i32 s2, s2, -1
